# baseline (speedup 1.0000x reference)
.LBB0_321:
	s_and_b64 vcc, exec, s[6:7]
	s_cbranch_vccz .LBB0_48
	s_setprio 1
	s_waitcnt lgkmcnt(0)
	v_or_b32_e32 v3, s3, v180
	v_readlane_b32 s0, v250, 13
	v_lshlrev_b32_e32 v4, 12, v3
	v_mov_b32_e32 v5, v2
	v_readlane_b32 s1, v250, 14
	s_add_i32 m0, s95, 0x4000
	v_lshlrev_b32_e32 v3, 4, v218
	v_lshl_add_u64 v[6:7], s[0:1], 0, v[4:5]
	v_lshlrev_b32_e32 v4, 4, v219
	v_lshl_add_u64 v[6:7], v[6:7], 0, v[4:5]
	global_load_dwordx4 v[82:85], v[6:7], off
	global_load_dwordx4 v[86:89], v[6:7], off offset:32
	global_load_dwordx4 v[90:93], v[6:7], off offset:64
	global_load_dwordx4 v[94:97], v[6:7], off offset:96
	global_load_dwordx4 v[98:101], v[6:7], off offset:128
	global_load_dwordx4 v[102:105], v[6:7], off offset:160
	global_load_dwordx4 v[106:109], v[6:7], off offset:192
	global_load_dwordx4 v[110:113], v[6:7], off offset:224
	v_lshlrev_b32_e32 v140, 8, v180
	global_load_lds_dwordx4 v[166:167], off
	s_add_i32 m0, s95, 0x4400
	v_mov_b32_e32 v18, v2
	global_load_lds_dwordx4 v[0:1], off
	v_and_b32_e32 v0, 0xf0, v3
	v_bitop3_b32 v1, v140, v4, v0 bitop3:0xf6
	s_waitcnt vmcnt(0) lgkmcnt(0)
	s_waitcnt vmcnt(0) lgkmcnt(0)
	s_barrier
	ds_read_b128 v[6:9], v1
	ds_read_b128 v[10:13], v1 offset:8192
	v_mov_b32_e32 v19, v18
	v_mov_b32_e32 v20, v18
	v_mov_b32_e32 v21, v18
	v_mov_b32_e32 v22, v18
	v_mov_b32_e32 v23, v18
	v_mov_b32_e32 v24, v18
	v_mov_b32_e32 v25, v18
	v_mov_b32_e32 v26, v18
	v_mov_b32_e32 v27, v18
	v_mov_b32_e32 v28, v18
	v_mov_b32_e32 v29, v18
	v_mov_b32_e32 v30, v18
	v_mov_b32_e32 v31, v18
	v_mov_b32_e32 v32, v18
	v_mov_b32_e32 v33, v18
	v_or_b32_e32 v1, 32, v4
	v_bitop3_b32 v1, v140, v1, v0 bitop3:0xf6
	s_movk_i32 s0, 0xf0
	v_bitop3_b32 v141, v4, v3, s0 bitop3:0x78
	s_movk_i32 s0, 0x60
	v_bitop3_b32 v144, v4, v0, s0 bitop3:0x36
	s_movk_i32 s0, 0x80
	v_bitop3_b32 v145, v4, v0, s0 bitop3:0x36
	s_movk_i32 s0, 0xa0
	v_bitop3_b32 v146, v4, v0, s0 bitop3:0x36
	s_movk_i32 s0, 0xc0
	v_bitop3_b32 v147, v4, v0, s0 bitop3:0x36
	s_movk_i32 s0, 0xe0
	v_bitop3_b32 v142, v4, v0, 32 bitop3:0x36
	v_bitop3_b32 v143, v4, v0, 64 bitop3:0x36
	v_bitop3_b32 v148, v4, v0, s0 bitop3:0x36
	s_lshl_b32 s0, s2, 2
	s_lshl_b32 s6, s13, 12
	s_movk_i32 s4, 0x4000
	s_mov_b32 s5, 0
	s_or_b32 s1, s3, 31
	v_mov_b32_e32 v153, 0xf149f2ca
	v_mov_b32_e32 v152, 0
	s_mov_b32 s73, 63
	s_mov_b64 s[92:93], 0
	s_mov_b32 s74, 0
	s_waitcnt lgkmcnt(1)
	v_mfma_f32_32x32x16_bf16 v[34:49], v[6:9], v[82:85], v[18:33]
	s_waitcnt lgkmcnt(0)
	v_mfma_f32_32x32x16_bf16 v[18:33], v[10:13], v[82:85], v[18:33]
	ds_read_b128 v[6:9], v1
	ds_read_b128 v[10:13], v1 offset:8192
	v_or_b32_e32 v1, 64, v4
	v_bitop3_b32 v1, v140, v1, v0 bitop3:0xf6
	s_waitcnt lgkmcnt(1)
	v_mfma_f32_32x32x16_bf16 v[34:49], v[6:9], v[86:89], v[34:49]
	s_waitcnt lgkmcnt(0)
	v_mfma_f32_32x32x16_bf16 v[18:33], v[10:13], v[86:89], v[18:33]
	ds_read_b128 v[6:9], v1
	ds_read_b128 v[10:13], v1 offset:8192
	v_or_b32_e32 v1, 0x60, v4
	v_bitop3_b32 v1, v140, v1, v0 bitop3:0xf6
	s_waitcnt lgkmcnt(1)
	v_mfma_f32_32x32x16_bf16 v[34:49], v[6:9], v[90:93], v[34:49]
	s_waitcnt lgkmcnt(0)
	v_mfma_f32_32x32x16_bf16 v[18:33], v[10:13], v[90:93], v[18:33]
	ds_read_b128 v[6:9], v1
	ds_read_b128 v[10:13], v1 offset:8192
	v_or_b32_e32 v1, 0x80, v4
	v_bitop3_b32 v1, v140, v1, v0 bitop3:0xf6
	s_waitcnt lgkmcnt(1)
	v_mfma_f32_32x32x16_bf16 v[34:49], v[6:9], v[94:97], v[34:49]
	s_waitcnt lgkmcnt(0)
	v_mfma_f32_32x32x16_bf16 v[18:33], v[10:13], v[94:97], v[18:33]
	ds_read_b128 v[6:9], v1
	ds_read_b128 v[10:13], v1 offset:8192
	v_or_b32_e32 v1, 0xa0, v4
	v_bitop3_b32 v1, v140, v1, v0 bitop3:0xf6
	s_waitcnt lgkmcnt(1)
	v_mfma_f32_32x32x16_bf16 v[34:49], v[6:9], v[98:101], v[34:49]
	s_waitcnt lgkmcnt(0)
	v_mfma_f32_32x32x16_bf16 v[18:33], v[10:13], v[98:101], v[18:33]
	ds_read_b128 v[6:9], v1
	ds_read_b128 v[10:13], v1 offset:8192
	v_or_b32_e32 v1, 0xc0, v4
	v_bitop3_b32 v1, v140, v1, v0 bitop3:0xf6
	s_waitcnt lgkmcnt(1)
	v_mfma_f32_32x32x16_bf16 v[34:49], v[6:9], v[102:105], v[34:49]
	s_waitcnt lgkmcnt(0)
	v_mfma_f32_32x32x16_bf16 v[18:33], v[10:13], v[102:105], v[18:33]
	ds_read_b128 v[6:9], v1
	ds_read_b128 v[10:13], v1 offset:8192
	v_or_b32_e32 v1, 0xe0, v4
	v_bitop3_b32 v0, v140, v1, v0 bitop3:0xf6
	v_mov_b32_e32 v1, v2
	s_waitcnt lgkmcnt(1)
	v_mfma_f32_32x32x16_bf16 v[34:49], v[6:9], v[106:109], v[34:49]
	s_waitcnt lgkmcnt(0)
	v_mfma_f32_32x32x16_bf16 v[18:33], v[10:13], v[106:109], v[18:33]
	ds_read_b128 v[4:7], v0
	ds_read_b128 v[8:11], v0 offset:8192
	v_lshl_add_u32 v0, v180, 2, s0
	s_lshl_b32 s0, s12, 6
	s_and_b32 s0, s0, 0xffffc000
	v_or_b32_e32 v149, 0x20000, v0
	s_or_b32 s72, s6, s0
	v_lshl_or_b32 v0, v216, 4, s6
	s_add_i32 s0, s8, s2
	v_or_b32_e32 v150, 0x18000, v0
	v_add_u32_e32 v0, s0, v180
	v_sub_u32_e32 v151, v0, v217
	v_lshlrev_b32_e32 v0, 11, v180
	s_waitcnt lgkmcnt(1)
	v_mfma_f32_32x32x16_bf16 v[34:49], v[4:7], v[110:113], v[34:49]
	v_and_b32_e32 v3, 0x8000, v0
	v_lshlrev_b32_e32 v6, 12, v215
	s_add_i32 s0, s11, 64
	v_add3_u32 v4, s0, v3, v6
	v_add3_u32 v4, v4, s10, v214
	v_add_lshl_u32 v4, v4, v213, 1
	v_mov_b32_e32 v5, v2
	s_waitcnt lgkmcnt(0)
	v_mfma_f32_32x32x16_bf16 v[18:33], v[8:11], v[110:113], v[18:33]
	s_add_i32 s0, s11, 0x4000
	v_add3_u32 v0, s11, v3, v6
	v_lshl_add_u64 v[130:131], s[88:89], 0, v[4:5]
	v_add3_u32 v4, s0, v3, v6
	s_addk_i32 s11, 0x4040
	v_add3_u32 v4, v4, s10, v214
	v_add3_u32 v3, s11, v3, v6
	v_add_lshl_u32 v4, v4, v213, 1
	v_add3_u32 v3, v3, s10, v214
	s_lshl_b32 s0, s8, 13
	s_lshl_b32 s8, s9, 16
	v_lshl_add_u64 v[132:133], s[88:89], 0, v[4:5]
	v_add_lshl_u32 v4, v3, v213, 1
	v_lshl_or_b32 v3, v181, 13, s8
	s_waitcnt vmcnt(0) lgkmcnt(0)
	v_add3_u32 v0, v0, s10, v214
	v_lshl_add_u64 v[134:135], s[88:89], 0, v[4:5]
	s_add_i32 s0, s0, 0x100000
	v_or_b32_e32 v4, v3, v182
	s_mov_b32 s8, 0x8000
	v_add_lshl_u32 v0, v0, v213, 1
	s_and_b32 s0, s0, 0x7f80000
	v_lshl_add_u64 v[136:137], s[90:91], 0, v[4:5]
	v_or3_b32 v4, v3, v183, s8
	v_cmp_gt_u32_e64 s[6:7], 32, v216
	v_lshl_add_u64 v[0:1], s[88:89], 0, v[0:1]
	s_add_u32 s0, s0, 0x80000
	v_lshl_add_u64 v[138:139], s[90:91], 0, v[4:5]
	s_barrier
	s_branch .LBB0_325

.LBB0_338:
	s_setprio 0
	s_and_saveexec_b64 s[8:9], s[6:7]
	s_cbranch_execz .LBB0_47
	v_lshlrev_b32_e32 v0, 2, v180
	v_lshl_add_u32 v0, s2, 2, v0
	v_or_b32_e32 v0, 0x20400, v0
	ds_write_b32 v0, v152
	s_branch .LBB0_47
